# dil combine slices rebalanced: 512 units per round, second round only on the first 768 items (was 683 units/item = a partial second round on every item)
# baseline (speedup 1.0000x reference)
; DI void dil_attn_phase(ldsp lds, const bf16_t* proj, bf16_t* og, float* lse, const float* rope, int nitems, const DilPrev pv, int tid_, int wid_, int lane_) {
;     ...
;         if (pv.og) {
;             constexpr int PIECE = (SLAB_ROWS * 96 + SLAB_B * 288 - 1) / (SLAB_B * 288);
;             const int u0 = it * PIECE, u1 = (u0 + PIECE < SLAB_ROWS * 96) ? u0 + PIECE : SLAB_ROWS * 96;
;             dil_combine(pv.og, pv.lse, pv.proj, pv.br, pv.b0, u0 + tid, u1, NTHREADS);
; DI void dil_combine(const bf16_t* og, const float* lse, const bf16_t* proj, bf16_t* br, int b0, int u0, int u1, int ustride) {
;     for (int u = u0; u < u1; u += ustride) {
;         const int row = u / 96, ch = u - row * 96, head = ch >> 4;
;         const float l0 = lse[(size_t)row * 18 + head], l1 = lse[(size_t)row * 18 + 6 + head], l2 = lse[(size_t)row * 18 + 12 + head];
;         const float m = fmaxf(l0, fmaxf(l1, l2));
;         float e0 = __expf(l0 - m), e1 = __expf(l1 - m), e2 = __expf(l2 - m);
;         const float is = 1.0f / (e0 + e1 + e2); e0 *= is; e1 *= is; e2 *= is;
;         const bf16_t* ob = og + (size_t)row * 2304 + ch * 8;
;         const u32x4 a = *(const u32x4*)ob, bq = *(const u32x4*)(ob + 768), c = *(const u32x4*)(ob + 1536);
;         const u32x4 gv = *(const u32x4*)(proj + (size_t)row * DIL_N + DB_GATE + ch * 8);
.LBB0_430:
	s_or_b64 exec, exec, s[26:27]
	s_andn2_b64 vcc, exec, s[50:51]
	s_cbranch_vccnz .LBB0_330
	s_lshl_b32 s17, s15, 9
	s_add_i32 s98, s17, 0x200
	s_cmpk_lt_u32 s15, 0x300
	s_cselect_b32 s15, 0x180000, s98
	v_add_u32_e32 v14, s17, v135
	v_cmp_gt_i32_e32 vcc, s15, v14
	s_and_saveexec_b64 s[26:27], vcc
	s_movk_i32 s17, 0xfd00
	s_movk_i32 s19, 0xffa0
	s_movk_i32 s34, 0x48
	s_movk_i32 s35, 0x1200
	s_cbranch_execz .LBB0_329
	v_lshlrev_b32_e32 v62, 3, v14
	s_mov_b64 s[30:31], 0
.LBB0_433:
	v_mul_hi_i32 v13, v14, s68
	v_lshrrev_b32_e32 v15, 31, v13
	v_ashrrev_i32_e32 v13, 4, v13
	v_add_u32_e32 v64, v13, v15
	v_mad_u64_u32 v[66:67], s[22:23], v64, s19, v[14:15]
	v_ashrrev_i32_e32 v66, 4, v66
	v_mov_b64_e32 v[68:69], s[44:45]
	v_ashrrev_i32_e32 v67, 31, v66
	v_mad_i64_i32 v[68:69], s[22:23], v64, s34, v[68:69]
	v_lshl_add_u64 v[66:67], v[66:67], 2, v[68:69]
	global_load_dword v13, v[66:67], off
	global_load_dword v15, v[66:67], off offset:24
	global_load_dword v33, v[66:67], off offset:48
	v_ashrrev_i32_e32 v65, 31, v64
	v_lshlrev_b64 v[80:81], 14, v[64:65]
	v_lshl_add_u64 v[80:81], s[52:53], 0, v[80:81]
	v_add_u32_e32 v14, 0x120000, v14
	v_mad_u64_u32 v[70:71], s[22:23], v64, s17, v[62:63]
	v_ashrrev_i32_e32 v71, 31, v70
	v_lshlrev_b64 v[88:89], 1, v[70:71]
	v_mov_b64_e32 v[68:69], s[40:41]
	v_lshl_add_u64 v[80:81], v[80:81], 0, v[88:89]
	v_mad_i64_i32 v[68:69], s[22:23], v64, s35, v[68:69]
	v_add_co_u32_e32 v80, vcc, s73, v80
	v_lshl_add_u64 v[76:77], v[68:69], 0, v[88:89]
	s_nop 0
	v_addc_co_u32_e32 v81, vcc, 0, v81, vcc
	global_load_dwordx4 v[68:71], v[76:77], off
	global_load_dwordx4 v[72:75], v[76:77], off offset:1536
	s_nop 0
	global_load_dwordx4 v[76:79], v[76:77], off offset:3072
	global_load_dwordx4 v[80:83], v[80:81], off offset:2048
	s_waitcnt vmcnt(4)
	v_max3_f32 v63, v13, v15, v33
	v_sub_f32_e32 v13, v13, v63
	v_mul_f32_e32 v13, 0x3fb8aa3b, v13
	v_exp_f32_e32 v85, v13
	v_sub_f32_e32 v13, v15, v63
	v_mul_f32_e32 v13, 0x3fb8aa3b, v13
	v_exp_f32_e32 v84, v13
	v_sub_f32_e32 v13, v33, v63
	v_mul_f32_e32 v13, 0x3fb8aa3b, v13
	v_exp_f32_e32 v13, v13
	v_add_f32_e32 v15, v85, v84
	v_add_f32_e32 v15, v13, v15
	v_div_scale_f32 v33, s[22:23], v15, v15, 1.0
	v_rcp_f32_e32 v63, v33
	s_nop 0
	v_fma_f32 v66, -v33, v63, 1.0
	v_fmac_f32_e32 v63, v66, v63
	v_div_scale_f32 v66, vcc, 1.0, v15, 1.0
	v_mul_f32_e32 v67, v66, v63
	v_fma_f32 v90, -v33, v67, v66
	v_fmac_f32_e32 v67, v90, v63
	v_fma_f32 v33, -v33, v67, v66
	s_nop 1
	v_div_fmas_f32 v33, v33, v63, v67
	v_div_fixup_f32 v86, v33, v15, 1.0
	v_mul_f32_e32 v66, v13, v86
	v_pk_mul_f32 v[84:85], v[84:85], v[86:87] op_sel_hi:[1,0]
	v_lshlrev_b64 v[64:65], 11, v[64:65]
	v_lshl_add_u64 v[64:65], s[54:55], 0, v[64:65]
	v_lshl_add_u64 v[64:65], v[64:65], 0, v[88:89]
	v_add_u32_e32 v62, 0x900000, v62
	s_waitcnt vmcnt(3)
	v_and_b32_e32 v87, 0xffff0000, v68
	v_lshlrev_b32_e32 v90, 16, v68
	s_waitcnt vmcnt(2)
	v_lshlrev_b32_e32 v86, 16, v72
	v_and_b32_e32 v91, 0xffff0000, v72
	s_waitcnt vmcnt(0)
; DI unsigned cvt_pk_bf16(float lo, float hi) { const f32x2_t v = {lo, hi}; const bf16v2_t b = __builtin_convertvector(v, bf16v2_t); return __builtin_bit_cast(unsigned, b); }
; DI float bf_lo(unsigned u) { return __uint_as_float(u << 16); }
; DI float bf_hi(unsigned u) { return __uint_as_float(u & 0xffff0000u); }
; DI float silu_f(float x) { return x / (1.0f + __expf(-x)); }
; DI void dil_combine(const bf16_t* og, const float* lse, const bf16_t* proj, bf16_t* br, int b0, int u0, int u1, int ustride) {
;     ...
;         u32x4 w;
; #pragma unroll
;         for (int e = 0; e < 4; ++e) {
;             const float vlo = e0 * bf_lo(a[e]) + e1 * bf_lo(bq[e]) + e2 * bf_lo(c[e]);
;             const float vhi = e0 * bf_hi(a[e]) + e1 * bf_hi(bq[e]) + e2 * bf_hi(c[e]);
;             w[e] = cvt_pk_bf16(vlo * silu_f(bf_lo(gv[e])), vhi * silu_f(bf_hi(gv[e])));
;         }
;         *(u32x4*)(br + ((size_t)b0 * SEQ + row) * 1024 + ch * 8) = w;
	v_lshlrev_b32_e32 v13, 16, v80
	v_and_b32_e32 v15, 0xffff0000, v80
	v_mul_f32_e32 v33, 0xbfb8aa3b, v13
	v_exp_f32_e32 v94, v33
	v_mul_f32_e32 v33, 0xbfb8aa3b, v15
	v_exp_f32_e32 v95, v33
	v_pk_mul_f32 v[90:91], v[84:85], v[90:91] op_sel:[1,0] op_sel_hi:[0,1]
	v_lshlrev_b32_e32 v92, 16, v76
	v_and_b32_e32 v93, 0xffff0000, v76
	v_pk_add_f32 v[94:95], v[94:95], 1.0 op_sel_hi:[1,0]
	v_pk_fma_f32 v[86:87], v[84:85], v[86:87], v[90:91]
	v_div_scale_f32 v33, s[22:23], v95, v95, v15
	v_rcp_f32_e32 v63, v33
	v_lshlrev_b32_e32 v76, 16, v77
	v_and_b32_e32 v77, 0xffff0000, v77
	v_fma_f32 v67, -v33, v63, 1.0
	v_fmac_f32_e32 v63, v67, v63
	v_div_scale_f32 v67, vcc, v15, v95, v15
	v_mul_f32_e32 v68, v67, v63
	v_fma_f32 v72, -v33, v68, v67
	v_fmac_f32_e32 v68, v72, v63
	v_fma_f32 v33, -v33, v68, v67
	v_div_fmas_f32 v33, v33, v63, v68
	v_div_fixup_f32 v95, v33, v95, v15
	v_div_scale_f32 v15, s[22:23], v94, v94, v13
	v_rcp_f32_e32 v33, v15
	v_lshlrev_b32_e32 v72, 16, v69
	v_fma_f32 v63, -v15, v33, 1.0
	v_fmac_f32_e32 v33, v63, v33
	v_div_scale_f32 v63, vcc, v13, v94, v13
	v_mul_f32_e32 v67, v63, v33
	v_fma_f32 v68, -v15, v67, v63
	v_fmac_f32_e32 v67, v68, v33
	v_fma_f32 v15, -v15, v67, v63
	v_div_fmas_f32 v15, v15, v33, v67
	v_div_fixup_f32 v94, v15, v94, v13
	v_lshlrev_b32_e32 v13, 16, v81
	v_and_b32_e32 v15, 0xffff0000, v81
	v_mul_f32_e32 v33, 0xbfb8aa3b, v13
	v_exp_f32_e32 v80, v33
	v_mul_f32_e32 v33, 0xbfb8aa3b, v15
	v_exp_f32_e32 v81, v33
	v_pk_fma_f32 v[86:87], v[66:67], v[92:93], v[86:87] op_sel_hi:[0,1,1]
	v_pk_mul_f32 v[86:87], v[94:95], v[86:87]
	v_pk_add_f32 v[80:81], v[80:81], 1.0 op_sel_hi:[1,0]
	s_nop 0
	v_div_scale_f32 v33, s[22:23], v81, v81, v15
	v_rcp_f32_e32 v63, v33
	v_cvt_pk_bf16_f32 v68, v86, v87
	v_and_b32_e32 v87, 0xffff0000, v69
	v_lshlrev_b32_e32 v86, 16, v73
	v_fma_f32 v67, -v33, v63, 1.0
	v_fmac_f32_e32 v63, v67, v63
	v_div_scale_f32 v67, vcc, v15, v81, v15
	v_mul_f32_e32 v69, v67, v63
	v_fma_f32 v90, -v33, v69, v67
	v_fmac_f32_e32 v69, v90, v63
	v_fma_f32 v33, -v33, v69, v67
	v_div_fmas_f32 v33, v33, v63, v69
	v_div_fixup_f32 v81, v33, v81, v15
	v_div_scale_f32 v15, s[22:23], v80, v80, v13
	v_rcp_f32_e32 v33, v15
	v_and_b32_e32 v73, 0xffff0000, v73
	v_pk_mul_f32 v[72:73], v[84:85], v[72:73] op_sel:[1,0] op_sel_hi:[0,1]
	v_pk_fma_f32 v[72:73], v[84:85], v[86:87], v[72:73]
	v_fma_f32 v63, -v15, v33, 1.0
	v_fmac_f32_e32 v33, v63, v33
	v_div_scale_f32 v63, vcc, v13, v80, v13
	v_mul_f32_e32 v67, v63, v33
	v_fma_f32 v69, -v15, v67, v63
	v_fmac_f32_e32 v67, v69, v33
	v_fma_f32 v15, -v15, v67, v63
	v_div_fmas_f32 v15, v15, v33, v67
	v_div_fixup_f32 v80, v15, v80, v13
	v_lshlrev_b32_e32 v13, 16, v82
	v_and_b32_e32 v15, 0xffff0000, v82
	v_mul_f32_e32 v33, 0xbfb8aa3b, v13
	v_exp_f32_e32 v86, v33
	v_mul_f32_e32 v33, 0xbfb8aa3b, v15
	v_exp_f32_e32 v87, v33
	v_pk_fma_f32 v[72:73], v[66:67], v[76:77], v[72:73] op_sel_hi:[0,1,1]
	v_pk_mul_f32 v[72:73], v[80:81], v[72:73]
	v_lshlrev_b32_e32 v76, 16, v70
	v_pk_add_f32 v[86:87], v[86:87], 1.0 op_sel_hi:[1,0]
	v_cvt_pk_bf16_f32 v69, v72, v73
	v_div_scale_f32 v33, s[22:23], v87, v87, v15
	v_rcp_f32_e32 v63, v33
	v_and_b32_e32 v73, 0xffff0000, v70
	v_lshlrev_b32_e32 v72, 16, v74
	v_and_b32_e32 v77, 0xffff0000, v74
	v_fma_f32 v67, -v33, v63, 1.0
	v_fmac_f32_e32 v63, v67, v63
	v_div_scale_f32 v67, vcc, v15, v87, v15
	v_mul_f32_e32 v70, v67, v63
	v_fma_f32 v74, -v33, v70, v67
	v_fmac_f32_e32 v70, v74, v63
	v_fma_f32 v33, -v33, v70, v67
	v_div_fmas_f32 v33, v33, v63, v70
	v_div_fixup_f32 v87, v33, v87, v15
	v_div_scale_f32 v15, s[22:23], v86, v86, v13
	v_rcp_f32_e32 v33, v15
	v_pk_mul_f32 v[76:77], v[84:85], v[76:77] op_sel:[1,0] op_sel_hi:[0,1]
	v_lshlrev_b32_e32 v80, 16, v78
	v_and_b32_e32 v81, 0xffff0000, v78
	v_fma_f32 v63, -v15, v33, 1.0
	v_fmac_f32_e32 v33, v63, v33
	v_div_scale_f32 v63, vcc, v13, v86, v13
	v_mul_f32_e32 v67, v63, v33
	v_fma_f32 v70, -v15, v67, v63
	v_fmac_f32_e32 v67, v70, v33
	v_fma_f32 v15, -v15, v67, v63
	v_div_fmas_f32 v15, v15, v33, v67
	v_pk_fma_f32 v[72:73], v[84:85], v[72:73], v[76:77]
	v_div_fixup_f32 v86, v15, v86, v13
	v_pk_fma_f32 v[72:73], v[66:67], v[80:81], v[72:73] op_sel_hi:[0,1,1]
	v_pk_mul_f32 v[72:73], v[86:87], v[72:73]
	v_lshlrev_b32_e32 v74, 16, v71
	v_cvt_pk_bf16_f32 v70, v72, v73
	v_lshlrev_b32_e32 v72, 16, v75
	v_and_b32_e32 v75, 0xffff0000, v75
	v_and_b32_e32 v73, 0xffff0000, v71
	v_pk_mul_f32 v[74:75], v[84:85], v[74:75] op_sel:[1,0] op_sel_hi:[0,1]
	v_lshlrev_b32_e32 v13, 16, v83
	v_pk_fma_f32 v[72:73], v[84:85], v[72:73], v[74:75]
	v_lshlrev_b32_e32 v74, 16, v79
	v_and_b32_e32 v75, 0xffff0000, v79
	v_and_b32_e32 v15, 0xffff0000, v83
	v_mul_f32_e32 v33, 0xbfb8aa3b, v13
	v_pk_fma_f32 v[66:67], v[66:67], v[74:75], v[72:73] op_sel_hi:[0,1,1]
	v_exp_f32_e32 v72, v33
	v_mul_f32_e32 v33, 0xbfb8aa3b, v15
	v_exp_f32_e32 v73, v33
	s_nop 0
	v_pk_add_f32 v[72:73], v[72:73], 1.0 op_sel_hi:[1,0]
	s_nop 0
	v_div_scale_f32 v33, s[22:23], v73, v73, v15
	v_rcp_f32_e32 v63, v33
	s_nop 0
	v_fma_f32 v71, -v33, v63, 1.0
	v_fmac_f32_e32 v63, v71, v63
	v_div_scale_f32 v71, vcc, v15, v73, v15
	v_mul_f32_e32 v74, v71, v63
	v_fma_f32 v75, -v33, v74, v71
	v_fmac_f32_e32 v74, v75, v63
	v_fma_f32 v33, -v33, v74, v71
	v_div_fmas_f32 v33, v33, v63, v74
	v_div_fixup_f32 v73, v33, v73, v15
	v_div_scale_f32 v15, s[22:23], v72, v72, v13
	v_rcp_f32_e32 v33, v15
	s_nop 0
	v_fma_f32 v63, -v15, v33, 1.0
	v_fmac_f32_e32 v33, v63, v33
	v_div_scale_f32 v63, vcc, v13, v72, v13
	v_mul_f32_e32 v71, v63, v33
	v_fma_f32 v74, -v15, v71, v63
	v_fmac_f32_e32 v71, v74, v33
	v_fma_f32 v15, -v15, v71, v63
	v_div_fmas_f32 v15, v15, v33, v71
	v_div_fixup_f32 v72, v15, v72, v13
	v_pk_mul_f32 v[66:67], v[72:73], v[66:67]
	v_cmp_le_i32_e32 vcc, s15, v14
	v_cvt_pk_bf16_f32 v71, v66, v67
	s_or_b64 s[30:31], vcc, s[30:31]
	global_store_dwordx4 v[64:65], v[68:71], off
	s_andn2_b64 exec, exec, s[30:31]
	s_cbranch_execnz .LBB0_433
	s_branch .LBB0_329
